# v83 + nt (non-temporal) on the f32 weight loads of the conversion items (P0 and G1 slot): read-once stream no longer displaces L2 contents
# speedup vs baseline: 1.0097x; 1.0097x over previous
; __device__ __forceinline__ void item_load(const TItem& t, float (&v)[64], float& kv, int lane) {
;     const int nblk = t.N / 64, kb = t.item / nblk, nb = t.item % nblk, k0 = 64 * kb, n0 = 64 * nb;
;     const float* src = t.W + (size_t)k0 * t.N + n0 + lane;
; #pragma unroll
;     for (int i = 0; i < 64; ++i) v[i] = src[(size_t)i * t.N];
;     kv = t.ks ? t.ks[k0 + lane] : 1.0f;
.LBB0_43:
	s_lshr_b32 s6, s8, 6
	v_cvt_f32_u32_e32 v1, s6
	s_sub_i32 s18, 0, s6
	s_abs_i32 s13, s24
	s_ashr_i32 s12, s24, 31
	v_rcp_iflag_f32_e32 v1, v1
	s_mov_b32 s7, 0
	s_mov_b32 s9, s7
	v_mov_b32_e32 v3, 0
	v_mul_f32_e32 v1, 0x4f7ffffe, v1
	v_cvt_u32_f32_e32 v1, v1
	v_lshlrev_b32_e32 v2, 2, v12
	v_readfirstlane_b32 s19, v1
	s_mul_i32 s18, s18, s19
	s_mul_hi_u32 s18, s19, s18
	s_add_i32 s19, s19, s18
	s_mul_hi_u32 s18, s13, s19
	s_mul_i32 s19, s18, s6
	s_sub_i32 s13, s13, s19
	s_add_i32 s20, s18, 1
	s_sub_i32 s19, s13, s6
	s_cmp_ge_u32 s13, s6
	s_cselect_b32 s18, s20, s18
	s_cselect_b32 s13, s19, s13
	s_add_i32 s19, s18, 1
	s_cmp_ge_u32 s13, s6
	s_cselect_b32 s13, s19, s18
	s_xor_b32 s13, s13, s12
	s_sub_i32 s12, s13, s12
	s_mul_i32 s13, s12, s6
	s_lshl_b32 s6, s12, 6
	s_sub_i32 s12, s24, s13
	s_ashr_i32 s13, s6, 31
	s_mul_i32 s13, s13, s8
	s_mul_hi_u32 s18, s6, s8
	s_add_i32 s19, s18, s13
	s_mul_i32 s18, s6, s8
	s_lshl_b32 s12, s12, 6
	s_lshl_b64 s[18:19], s[18:19], 2
	s_add_u32 s18, s30, s18
	s_addc_u32 s19, s31, s19
	s_ashr_i32 s13, s12, 31
	s_lshl_b64 s[12:13], s[12:13], 2
	s_add_u32 s28, s18, s12
	s_addc_u32 s29, s19, s13
	v_lshl_add_u64 v[4:5], s[28:29], 0, v[2:3]
	s_lshl_b64 s[30:31], s[8:9], 2
	v_lshl_add_u64 v[4:5], v[4:5], 0, s[30:31]
	v_lshl_add_u64 v[6:7], v[4:5], 0, s[30:31]
	v_lshl_add_u64 v[8:9], v[6:7], 0, s[30:31]
	v_lshl_add_u64 v[10:11], v[8:9], 0, s[30:31]
	v_lshl_add_u64 v[14:15], v[10:11], 0, s[30:31]
	v_lshl_add_u64 v[16:17], v[14:15], 0, s[30:31]
	v_lshl_add_u64 v[18:19], v[16:17], 0, s[30:31]
	global_load_dword v29, v[4:5], off nt
	global_load_dword v30, v[6:7], off nt
	global_load_dword v31, v[8:9], off nt
	global_load_dword v32, v[10:11], off nt
	global_load_dword v33, v[14:15], off nt
	global_load_dword v34, v[16:17], off nt
	global_load_dword v35, v[18:19], off nt
	v_lshl_add_u64 v[4:5], v[18:19], 0, s[30:31]
	global_load_dword v36, v[4:5], off nt
	v_lshl_add_u64 v[4:5], v[4:5], 0, s[30:31]
	global_load_dword v37, v[4:5], off nt
	v_lshl_add_u64 v[4:5], v[4:5], 0, s[30:31]
	global_load_dword v38, v[4:5], off nt
	v_lshl_add_u64 v[4:5], v[4:5], 0, s[30:31]
	global_load_dword v39, v[4:5], off nt
	v_lshl_add_u64 v[4:5], v[4:5], 0, s[30:31]
	global_load_dword v40, v[4:5], off nt
	v_lshl_add_u64 v[4:5], v[4:5], 0, s[30:31]
	global_load_dword v41, v[4:5], off nt
	v_lshl_add_u64 v[4:5], v[4:5], 0, s[30:31]
	global_load_dword v42, v[4:5], off nt
	v_lshl_add_u64 v[4:5], v[4:5], 0, s[30:31]
	global_load_dword v43, v[4:5], off nt
	v_lshl_add_u64 v[4:5], v[4:5], 0, s[30:31]
	global_load_dword v44, v[4:5], off nt
	v_lshl_add_u64 v[4:5], v[4:5], 0, s[30:31]
	global_load_dword v45, v[4:5], off nt
	v_lshl_add_u64 v[4:5], v[4:5], 0, s[30:31]
	global_load_dword v46, v[4:5], off nt
	v_lshl_add_u64 v[4:5], v[4:5], 0, s[30:31]
	global_load_dword v47, v[4:5], off nt
	v_lshl_add_u64 v[4:5], v[4:5], 0, s[30:31]
	global_load_dword v48, v[4:5], off nt
	v_lshl_add_u64 v[4:5], v[4:5], 0, s[30:31]
	global_load_dword v49, v[4:5], off nt
	v_lshl_add_u64 v[4:5], v[4:5], 0, s[30:31]
	global_load_dword v50, v[4:5], off nt
	v_lshl_add_u64 v[4:5], v[4:5], 0, s[30:31]
	global_load_dword v51, v[4:5], off nt
	v_lshl_add_u64 v[4:5], v[4:5], 0, s[30:31]
	global_load_dword v52, v[4:5], off nt
	v_lshl_add_u64 v[4:5], v[4:5], 0, s[30:31]
	global_load_dword v53, v[4:5], off nt
	v_lshl_add_u64 v[4:5], v[4:5], 0, s[30:31]
	global_load_dword v54, v[4:5], off nt
	v_lshl_add_u64 v[4:5], v[4:5], 0, s[30:31]
	global_load_dword v55, v[4:5], off nt
	v_lshl_add_u64 v[4:5], v[4:5], 0, s[30:31]
	global_load_dword v56, v[4:5], off nt
	v_lshl_add_u64 v[4:5], v[4:5], 0, s[30:31]
	global_load_dword v57, v[4:5], off nt
	v_lshl_add_u64 v[4:5], v[4:5], 0, s[30:31]
	global_load_dword v58, v[4:5], off nt
	v_lshl_add_u64 v[4:5], v[4:5], 0, s[30:31]
	global_load_dword v60, v[4:5], off nt
	v_lshl_add_u64 v[4:5], v[4:5], 0, s[30:31]
	global_load_dword v61, v[4:5], off nt
	v_lshl_add_u64 v[4:5], v[4:5], 0, s[30:31]
	global_load_dword v62, v[4:5], off nt
	v_lshl_add_u64 v[4:5], v[4:5], 0, s[30:31]
	global_load_dword v63, v[4:5], off nt
	v_lshl_add_u64 v[4:5], v[4:5], 0, s[30:31]
	global_load_dword v64, v[4:5], off nt
	v_lshl_add_u64 v[4:5], v[4:5], 0, s[30:31]
	global_load_dword v65, v[4:5], off nt
	v_lshl_add_u64 v[4:5], v[4:5], 0, s[30:31]
	global_load_dword v66, v[4:5], off nt
	v_lshl_add_u64 v[4:5], v[4:5], 0, s[30:31]
	global_load_dword v67, v[4:5], off nt
	v_lshl_add_u64 v[4:5], v[4:5], 0, s[30:31]
	global_load_dword v68, v[4:5], off nt
	v_lshl_add_u64 v[4:5], v[4:5], 0, s[30:31]
	global_load_dword v69, v[4:5], off nt
	v_lshl_add_u64 v[4:5], v[4:5], 0, s[30:31]
	global_load_dword v70, v[4:5], off nt
	v_lshl_add_u64 v[4:5], v[4:5], 0, s[30:31]
	global_load_dword v71, v[4:5], off nt
	v_lshl_add_u64 v[4:5], v[4:5], 0, s[30:31]
	global_load_dword v72, v[4:5], off nt
	v_lshl_add_u64 v[4:5], v[4:5], 0, s[30:31]
	global_load_dword v73, v[4:5], off nt
	v_lshl_add_u64 v[4:5], v[4:5], 0, s[30:31]
	global_load_dword v74, v[4:5], off nt
	v_lshl_add_u64 v[4:5], v[4:5], 0, s[30:31]
	global_load_dword v75, v[4:5], off nt
	v_lshl_add_u64 v[4:5], v[4:5], 0, s[30:31]
	global_load_dword v76, v[4:5], off nt
	v_lshl_add_u64 v[4:5], v[4:5], 0, s[30:31]
	global_load_dword v77, v[4:5], off nt
	v_lshl_add_u64 v[4:5], v[4:5], 0, s[30:31]
	global_load_dword v78, v[4:5], off nt
	v_lshl_add_u64 v[4:5], v[4:5], 0, s[30:31]
	global_load_dword v79, v[4:5], off nt
	v_lshl_add_u64 v[4:5], v[4:5], 0, s[30:31]
	global_load_dword v80, v[4:5], off nt
	v_lshl_add_u64 v[4:5], v[4:5], 0, s[30:31]
	global_load_dword v81, v[4:5], off nt
	v_lshl_add_u64 v[4:5], v[4:5], 0, s[30:31]
	global_load_dword v82, v[4:5], off nt
	v_lshl_add_u64 v[4:5], v[4:5], 0, s[30:31]
	global_load_dword v83, v[4:5], off nt
	v_lshl_add_u64 v[4:5], v[4:5], 0, s[30:31]
	global_load_dword v84, v[4:5], off nt
	v_lshl_add_u64 v[4:5], v[4:5], 0, s[30:31]
	global_load_dword v85, v[4:5], off nt
	v_lshl_add_u64 v[4:5], v[4:5], 0, s[30:31]
	global_load_dword v86, v[4:5], off nt
	v_lshl_add_u64 v[4:5], v[4:5], 0, s[30:31]
	global_load_dword v87, v[4:5], off nt
	v_lshl_add_u64 v[4:5], v[4:5], 0, s[30:31]
	global_load_dword v88, v[4:5], off nt
	v_lshl_add_u64 v[4:5], v[4:5], 0, s[30:31]
	global_load_dword v89, v[4:5], off nt
	v_lshl_add_u64 v[4:5], v[4:5], 0, s[30:31]
	global_load_dword v90, v[4:5], off nt
	v_lshl_add_u64 v[4:5], v[4:5], 0, s[30:31]
	global_load_dword v91, v[4:5], off nt
	v_lshl_add_u64 v[4:5], v[4:5], 0, s[30:31]
	global_load_dword v92, v[4:5], off nt
	global_load_dword v59, v2, s[28:29]
	s_cmp_eq_u64 s[10:11], 0
	s_cbranch_scc1 .LBB0_45
	v_or_b32_e32 v4, s6, v12
	v_ashrrev_i32_e32 v5, 31, v4
	v_lshl_add_u64 v[4:5], v[4:5], 2, s[10:11]
	global_load_dword v93, v[4:5], off
	s_branch .LBB0_46

; __device__ __forceinline__ void item_load(const TItem& t, float (&v)[64], float& kv, int lane) {
;     const int nblk = t.N / 64, kb = t.item / nblk, nb = t.item % nblk, k0 = 64 * kb, n0 = 64 * nb;
;     const float* src = t.W + (size_t)k0 * t.N + n0 + lane;
; #pragma unroll
;     for (int i = 0; i < 64; ++i) v[i] = src[(size_t)i * t.N];
;     kv = t.ks ? t.ks[k0 + lane] : 1.0f;
.LBB0_79:
	s_lshr_b32 s9, s6, 6
	v_cvt_f32_u32_e32 v1, s9
	s_sub_i32 s12, 0, s9
	s_abs_i32 s11, s25
	s_ashr_i32 s10, s25, 31
	v_rcp_iflag_f32_e32 v1, v1
	s_nop 0
	v_mul_f32_e32 v1, 0x4f7ffffe, v1
	v_cvt_u32_f32_e32 v1, v1
	s_nop 0
	v_readfirstlane_b32 s13, v1
	s_mul_i32 s12, s12, s13
	s_mul_hi_u32 s12, s13, s12
	s_add_i32 s13, s13, s12
	s_mul_hi_u32 s12, s11, s13
	s_mul_i32 s13, s12, s9
	s_sub_i32 s11, s11, s13
	s_add_i32 s33, s12, 1
	s_sub_i32 s13, s11, s9
	s_cmp_ge_u32 s11, s9
	s_cselect_b32 s12, s33, s12
	s_cselect_b32 s11, s13, s11
	s_add_i32 s13, s12, 1
	s_cmp_ge_u32 s11, s9
	s_cselect_b32 s11, s13, s12
	s_xor_b32 s11, s11, s10
	s_sub_i32 s10, s11, s10
	s_mul_i32 s11, s10, s9
	s_lshl_b32 s9, s10, 6
	s_sub_i32 s10, s25, s11
	s_ashr_i32 s11, s9, 31
	s_mul_hi_u32 s12, s9, s6
	s_mul_i32 s11, s11, s6
	s_add_i32 s13, s12, s11
	s_mul_i32 s12, s9, s6
	s_lshl_b32 s10, s10, 6
	s_lshl_b64 s[12:13], s[12:13], 2
	s_add_u32 s12, s54, s12
	s_addc_u32 s13, s55, s13
	s_ashr_i32 s11, s10, 31
	s_lshl_b64 s[10:11], s[10:11], 2
	s_add_u32 s10, s12, s10
	s_addc_u32 s11, s13, s11
	v_lshl_add_u64 v[4:5], s[10:11], 0, v[2:3]
	global_load_dword v59, v2, s[10:11]
	s_lshl_b64 s[10:11], s[6:7], 2
	v_lshl_add_u64 v[4:5], v[4:5], 0, s[10:11]
	v_lshl_add_u64 v[6:7], v[4:5], 0, s[10:11]
	v_lshl_add_u64 v[8:9], v[6:7], 0, s[10:11]
	v_lshl_add_u64 v[10:11], v[8:9], 0, s[10:11]
	v_lshl_add_u64 v[34:35], v[10:11], 0, s[10:11]
	v_lshl_add_u64 v[36:37], v[34:35], 0, s[10:11]
	v_lshl_add_u64 v[38:39], v[36:37], 0, s[10:11]
	global_load_dword v29, v[4:5], off nt
	global_load_dword v30, v[6:7], off nt
	global_load_dword v31, v[8:9], off nt
	global_load_dword v32, v[10:11], off nt
	global_load_dword v33, v[34:35], off nt
	s_nop 0
	global_load_dword v34, v[36:37], off nt
	global_load_dword v35, v[38:39], off nt
	v_lshl_add_u64 v[4:5], v[38:39], 0, s[10:11]
	global_load_dword v36, v[4:5], off nt
	v_lshl_add_u64 v[4:5], v[4:5], 0, s[10:11]
	global_load_dword v37, v[4:5], off nt
	v_lshl_add_u64 v[4:5], v[4:5], 0, s[10:11]
	global_load_dword v38, v[4:5], off nt
	v_lshl_add_u64 v[4:5], v[4:5], 0, s[10:11]
	global_load_dword v39, v[4:5], off nt
	v_lshl_add_u64 v[4:5], v[4:5], 0, s[10:11]
	global_load_dword v40, v[4:5], off nt
	v_lshl_add_u64 v[4:5], v[4:5], 0, s[10:11]
	global_load_dword v41, v[4:5], off nt
	v_lshl_add_u64 v[4:5], v[4:5], 0, s[10:11]
	global_load_dword v42, v[4:5], off nt
	v_lshl_add_u64 v[4:5], v[4:5], 0, s[10:11]
	global_load_dword v43, v[4:5], off nt
	v_lshl_add_u64 v[4:5], v[4:5], 0, s[10:11]
	global_load_dword v44, v[4:5], off nt
	v_lshl_add_u64 v[4:5], v[4:5], 0, s[10:11]
	global_load_dword v45, v[4:5], off nt
	v_lshl_add_u64 v[4:5], v[4:5], 0, s[10:11]
	global_load_dword v46, v[4:5], off nt
	v_lshl_add_u64 v[4:5], v[4:5], 0, s[10:11]
	global_load_dword v47, v[4:5], off nt
	v_lshl_add_u64 v[4:5], v[4:5], 0, s[10:11]
	global_load_dword v48, v[4:5], off nt
	v_lshl_add_u64 v[4:5], v[4:5], 0, s[10:11]
	global_load_dword v49, v[4:5], off nt
	v_lshl_add_u64 v[4:5], v[4:5], 0, s[10:11]
	global_load_dword v50, v[4:5], off nt
	v_lshl_add_u64 v[4:5], v[4:5], 0, s[10:11]
	global_load_dword v51, v[4:5], off nt
	v_lshl_add_u64 v[4:5], v[4:5], 0, s[10:11]
	global_load_dword v52, v[4:5], off nt
	v_lshl_add_u64 v[4:5], v[4:5], 0, s[10:11]
	global_load_dword v53, v[4:5], off nt
	v_lshl_add_u64 v[4:5], v[4:5], 0, s[10:11]
	global_load_dword v54, v[4:5], off nt
	v_lshl_add_u64 v[4:5], v[4:5], 0, s[10:11]
	global_load_dword v55, v[4:5], off nt
	v_lshl_add_u64 v[4:5], v[4:5], 0, s[10:11]
	global_load_dword v56, v[4:5], off nt
	v_lshl_add_u64 v[4:5], v[4:5], 0, s[10:11]
	global_load_dword v57, v[4:5], off nt
	v_lshl_add_u64 v[4:5], v[4:5], 0, s[10:11]
	global_load_dword v58, v[4:5], off nt
	v_lshl_add_u64 v[4:5], v[4:5], 0, s[10:11]
	global_load_dword v60, v[4:5], off nt
	v_lshl_add_u64 v[4:5], v[4:5], 0, s[10:11]
	global_load_dword v61, v[4:5], off nt
	v_lshl_add_u64 v[4:5], v[4:5], 0, s[10:11]
	global_load_dword v62, v[4:5], off nt
	v_lshl_add_u64 v[4:5], v[4:5], 0, s[10:11]
	global_load_dword v63, v[4:5], off nt
	v_lshl_add_u64 v[4:5], v[4:5], 0, s[10:11]
	global_load_dword v64, v[4:5], off nt
	v_lshl_add_u64 v[4:5], v[4:5], 0, s[10:11]
	global_load_dword v65, v[4:5], off nt
	v_lshl_add_u64 v[4:5], v[4:5], 0, s[10:11]
	global_load_dword v66, v[4:5], off nt
	v_lshl_add_u64 v[4:5], v[4:5], 0, s[10:11]
	global_load_dword v67, v[4:5], off nt
	v_lshl_add_u64 v[4:5], v[4:5], 0, s[10:11]
	global_load_dword v68, v[4:5], off nt
	v_lshl_add_u64 v[4:5], v[4:5], 0, s[10:11]
	global_load_dword v69, v[4:5], off nt
	v_lshl_add_u64 v[4:5], v[4:5], 0, s[10:11]
	global_load_dword v70, v[4:5], off nt
	v_lshl_add_u64 v[4:5], v[4:5], 0, s[10:11]
	global_load_dword v71, v[4:5], off nt
	v_lshl_add_u64 v[4:5], v[4:5], 0, s[10:11]
	global_load_dword v72, v[4:5], off nt
	v_lshl_add_u64 v[4:5], v[4:5], 0, s[10:11]
	global_load_dword v73, v[4:5], off nt
	v_lshl_add_u64 v[4:5], v[4:5], 0, s[10:11]
	global_load_dword v74, v[4:5], off nt
	v_lshl_add_u64 v[4:5], v[4:5], 0, s[10:11]
	global_load_dword v75, v[4:5], off nt
	v_lshl_add_u64 v[4:5], v[4:5], 0, s[10:11]
	global_load_dword v76, v[4:5], off nt
	v_lshl_add_u64 v[4:5], v[4:5], 0, s[10:11]
	global_load_dword v77, v[4:5], off nt
	v_lshl_add_u64 v[4:5], v[4:5], 0, s[10:11]
	global_load_dword v78, v[4:5], off nt
	v_lshl_add_u64 v[4:5], v[4:5], 0, s[10:11]
	global_load_dword v79, v[4:5], off nt
	v_lshl_add_u64 v[4:5], v[4:5], 0, s[10:11]
	global_load_dword v80, v[4:5], off nt
	v_lshl_add_u64 v[4:5], v[4:5], 0, s[10:11]
	global_load_dword v81, v[4:5], off nt
	v_lshl_add_u64 v[4:5], v[4:5], 0, s[10:11]
	global_load_dword v82, v[4:5], off nt
	v_lshl_add_u64 v[4:5], v[4:5], 0, s[10:11]
	global_load_dword v83, v[4:5], off nt
	v_lshl_add_u64 v[4:5], v[4:5], 0, s[10:11]
	global_load_dword v84, v[4:5], off nt
	v_lshl_add_u64 v[4:5], v[4:5], 0, s[10:11]
	global_load_dword v85, v[4:5], off nt
	v_lshl_add_u64 v[4:5], v[4:5], 0, s[10:11]
	global_load_dword v86, v[4:5], off nt
	v_lshl_add_u64 v[4:5], v[4:5], 0, s[10:11]
	global_load_dword v87, v[4:5], off nt
	v_lshl_add_u64 v[4:5], v[4:5], 0, s[10:11]
	global_load_dword v88, v[4:5], off nt
	v_lshl_add_u64 v[4:5], v[4:5], 0, s[10:11]
	global_load_dword v89, v[4:5], off nt
	v_lshl_add_u64 v[4:5], v[4:5], 0, s[10:11]
	global_load_dword v90, v[4:5], off nt
	v_lshl_add_u64 v[4:5], v[4:5], 0, s[10:11]
	global_load_dword v91, v[4:5], off nt
	v_lshl_add_u64 v[4:5], v[4:5], 0, s[10:11]
	global_load_dword v92, v[4:5], off nt
	s_cmp_eq_u64 s[56:57], 0
	s_mov_b64 s[10:11], 0
	s_cbranch_scc1 .LBB0_82
	v_or_b32_e32 v4, s9, v12
	v_ashrrev_i32_e32 v5, 31, v4
	v_lshl_add_u64 v[4:5], v[4:5], 2, s[56:57]
	global_load_dword v93, v[4:5], off
	s_mov_b64 s[10:11], s[56:57]
	s_branch .LBB0_83

; __device__ __forceinline__ void item_load(const TItem& t, float (&v)[64], float& kv, int lane) {
;     const int nblk = t.N / 64, kb = t.item / nblk, nb = t.item % nblk, k0 = 64 * kb, n0 = 64 * nb;
;     const float* src = t.W + (size_t)k0 * t.N + n0 + lane;
; #pragma unroll
;     for (int i = 0; i < 64; ++i) v[i] = src[(size_t)i * t.N];
;     kv = t.ks ? t.ks[k0 + lane] : 1.0f;
.LBB0_298:
	s_lshr_b32 s9, s44, 6
	v_cvt_f32_u32_e32 v1, s9
	s_sub_i32 s16, 0, s9
	s_abs_i32 s15, s39
	s_ashr_i32 s14, s39, 31
	v_rcp_iflag_f32_e32 v1, v1
	v_readlane_b32 s24, v255, 2
	v_readlane_b32 s25, v255, 3
	s_mov_b32 s45, s25
	v_mul_f32_e32 v1, 0x4f7ffffe, v1
	v_cvt_u32_f32_e32 v1, v1
	v_readlane_b32 s26, v255, 4
	v_readlane_b32 s27, v255, 5
	v_readfirstlane_b32 s17, v1
	s_mul_i32 s16, s16, s17
	s_mul_hi_u32 s16, s17, s16
	s_add_i32 s17, s17, s16
	s_mul_hi_u32 s16, s15, s17
	s_mul_i32 s17, s16, s9
	s_sub_i32 s15, s15, s17
	s_add_i32 s17, s16, 1
	s_sub_i32 s18, s15, s9
	s_cmp_ge_u32 s15, s9
	s_cselect_b32 s16, s17, s16
	s_cselect_b32 s15, s18, s15
	s_add_i32 s17, s16, 1
	s_cmp_ge_u32 s15, s9
	s_cselect_b32 s15, s17, s16
	s_xor_b32 s15, s15, s14
	s_sub_i32 s14, s15, s14
	s_lshl_b32 s16, s14, 6
	s_ashr_i32 s15, s16, 31
	s_mul_i32 s9, s14, s9
	s_mul_i32 s15, s15, s44
	s_mul_hi_u32 s17, s16, s44
	s_sub_i32 s9, s39, s9
	s_add_i32 s19, s17, s15
	s_mul_i32 s18, s16, s44
	s_lshl_b32 s14, s9, 6
	s_lshl_b64 s[18:19], s[18:19], 2
	s_add_u32 s17, s12, s18
	s_addc_u32 s18, s13, s19
	s_ashr_i32 s15, s14, 31
	s_lshl_b64 s[12:13], s[14:15], 2
	s_add_u32 s12, s17, s12
	s_addc_u32 s13, s18, s13
	v_ashrrev_i32_e32 v1, 31, v0
	v_lshl_add_u64 v[2:3], v[0:1], 2, s[12:13]
	s_lshl_b64 s[12:13], s[44:45], 2
	global_load_dword v28, v[2:3], off nt
	v_lshl_add_u64 v[2:3], v[2:3], 0, s[12:13]
	global_load_dword v29, v[2:3], off nt
	v_lshl_add_u64 v[2:3], v[2:3], 0, s[12:13]
	global_load_dword v30, v[2:3], off nt
	v_lshl_add_u64 v[2:3], v[2:3], 0, s[12:13]
	global_load_dword v31, v[2:3], off nt
	v_lshl_add_u64 v[2:3], v[2:3], 0, s[12:13]
	global_load_dword v34, v[2:3], off nt
	v_lshl_add_u64 v[2:3], v[2:3], 0, s[12:13]
	global_load_dword v35, v[2:3], off nt
	v_lshl_add_u64 v[2:3], v[2:3], 0, s[12:13]
	global_load_dword v36, v[2:3], off nt
	v_lshl_add_u64 v[2:3], v[2:3], 0, s[12:13]
	global_load_dword v37, v[2:3], off nt
	v_lshl_add_u64 v[2:3], v[2:3], 0, s[12:13]
	global_load_dword v38, v[2:3], off nt
	v_lshl_add_u64 v[2:3], v[2:3], 0, s[12:13]
	global_load_dword v39, v[2:3], off nt
	v_lshl_add_u64 v[2:3], v[2:3], 0, s[12:13]
	global_load_dword v40, v[2:3], off nt
	v_lshl_add_u64 v[2:3], v[2:3], 0, s[12:13]
	global_load_dword v41, v[2:3], off nt
	v_lshl_add_u64 v[2:3], v[2:3], 0, s[12:13]
	global_load_dword v42, v[2:3], off nt
	v_lshl_add_u64 v[2:3], v[2:3], 0, s[12:13]
	global_load_dword v43, v[2:3], off nt
	v_lshl_add_u64 v[2:3], v[2:3], 0, s[12:13]
	global_load_dword v44, v[2:3], off nt
	v_lshl_add_u64 v[2:3], v[2:3], 0, s[12:13]
	global_load_dword v45, v[2:3], off nt
	v_lshl_add_u64 v[2:3], v[2:3], 0, s[12:13]
	global_load_dword v46, v[2:3], off nt
	v_lshl_add_u64 v[2:3], v[2:3], 0, s[12:13]
	global_load_dword v47, v[2:3], off nt
	v_lshl_add_u64 v[2:3], v[2:3], 0, s[12:13]
	global_load_dword v48, v[2:3], off nt
	v_lshl_add_u64 v[2:3], v[2:3], 0, s[12:13]
	global_load_dword v49, v[2:3], off nt
	v_lshl_add_u64 v[2:3], v[2:3], 0, s[12:13]
	global_load_dword v50, v[2:3], off nt
	v_lshl_add_u64 v[2:3], v[2:3], 0, s[12:13]
	global_load_dword v51, v[2:3], off nt
	v_lshl_add_u64 v[2:3], v[2:3], 0, s[12:13]
	global_load_dword v52, v[2:3], off nt
	v_lshl_add_u64 v[2:3], v[2:3], 0, s[12:13]
	global_load_dword v53, v[2:3], off nt
	v_lshl_add_u64 v[2:3], v[2:3], 0, s[12:13]
	global_load_dword v54, v[2:3], off nt
	v_lshl_add_u64 v[2:3], v[2:3], 0, s[12:13]
	global_load_dword v55, v[2:3], off nt
	v_lshl_add_u64 v[2:3], v[2:3], 0, s[12:13]
	global_load_dword v56, v[2:3], off nt
	v_lshl_add_u64 v[2:3], v[2:3], 0, s[12:13]
	global_load_dword v57, v[2:3], off nt
	v_lshl_add_u64 v[2:3], v[2:3], 0, s[12:13]
	global_load_dword v58, v[2:3], off nt
	v_lshl_add_u64 v[2:3], v[2:3], 0, s[12:13]
	global_load_dword v59, v[2:3], off nt
	v_lshl_add_u64 v[2:3], v[2:3], 0, s[12:13]
	global_load_dword v60, v[2:3], off nt
	v_lshl_add_u64 v[2:3], v[2:3], 0, s[12:13]
	global_load_dword v61, v[2:3], off nt
	v_lshl_add_u64 v[2:3], v[2:3], 0, s[12:13]
	global_load_dword v62, v[2:3], off nt
	v_lshl_add_u64 v[2:3], v[2:3], 0, s[12:13]
	global_load_dword v63, v[2:3], off nt
	v_lshl_add_u64 v[2:3], v[2:3], 0, s[12:13]
	global_load_dword v64, v[2:3], off nt
	v_lshl_add_u64 v[2:3], v[2:3], 0, s[12:13]
	global_load_dword v65, v[2:3], off nt
	v_lshl_add_u64 v[2:3], v[2:3], 0, s[12:13]
	global_load_dword v66, v[2:3], off nt
	v_lshl_add_u64 v[2:3], v[2:3], 0, s[12:13]
	global_load_dword v67, v[2:3], off nt
	v_lshl_add_u64 v[2:3], v[2:3], 0, s[12:13]
	global_load_dword v68, v[2:3], off nt
	v_lshl_add_u64 v[2:3], v[2:3], 0, s[12:13]
	global_load_dword v69, v[2:3], off nt
	v_lshl_add_u64 v[2:3], v[2:3], 0, s[12:13]
	global_load_dword v70, v[2:3], off nt
	v_lshl_add_u64 v[2:3], v[2:3], 0, s[12:13]
	global_load_dword v71, v[2:3], off nt
	v_lshl_add_u64 v[2:3], v[2:3], 0, s[12:13]
	global_load_dword v72, v[2:3], off nt
	v_lshl_add_u64 v[2:3], v[2:3], 0, s[12:13]
	global_load_dword v73, v[2:3], off nt
	v_lshl_add_u64 v[2:3], v[2:3], 0, s[12:13]
	global_load_dword v74, v[2:3], off nt
	v_lshl_add_u64 v[2:3], v[2:3], 0, s[12:13]
	global_load_dword v75, v[2:3], off nt
	v_lshl_add_u64 v[2:3], v[2:3], 0, s[12:13]
	global_load_dword v76, v[2:3], off nt
	v_lshl_add_u64 v[2:3], v[2:3], 0, s[12:13]
	global_load_dword v77, v[2:3], off nt
	v_lshl_add_u64 v[2:3], v[2:3], 0, s[12:13]
	global_load_dword v78, v[2:3], off nt
	v_lshl_add_u64 v[2:3], v[2:3], 0, s[12:13]
	global_load_dword v79, v[2:3], off nt
	v_lshl_add_u64 v[2:3], v[2:3], 0, s[12:13]
	global_load_dword v80, v[2:3], off nt
	v_lshl_add_u64 v[2:3], v[2:3], 0, s[12:13]
	global_load_dword v81, v[2:3], off nt
	v_lshl_add_u64 v[2:3], v[2:3], 0, s[12:13]
	global_load_dword v82, v[2:3], off nt
	v_lshl_add_u64 v[2:3], v[2:3], 0, s[12:13]
	global_load_dword v83, v[2:3], off nt
	v_lshl_add_u64 v[2:3], v[2:3], 0, s[12:13]
	global_load_dword v84, v[2:3], off nt
	v_lshl_add_u64 v[2:3], v[2:3], 0, s[12:13]
	global_load_dword v85, v[2:3], off nt
	v_lshl_add_u64 v[2:3], v[2:3], 0, s[12:13]
	global_load_dword v86, v[2:3], off nt
	v_lshl_add_u64 v[2:3], v[2:3], 0, s[12:13]
	global_load_dword v87, v[2:3], off nt
	v_lshl_add_u64 v[2:3], v[2:3], 0, s[12:13]
	global_load_dword v88, v[2:3], off nt
	v_lshl_add_u64 v[2:3], v[2:3], 0, s[12:13]
	global_load_dword v89, v[2:3], off nt
	v_lshl_add_u64 v[2:3], v[2:3], 0, s[12:13]
	global_load_dword v90, v[2:3], off nt
	v_lshl_add_u64 v[2:3], v[2:3], 0, s[12:13]
	global_load_dword v91, v[2:3], off nt
	v_lshl_add_u64 v[2:3], v[2:3], 0, s[12:13]
	global_load_dword v92, v[2:3], off nt
	v_lshl_add_u64 v[2:3], v[2:3], 0, s[12:13]
	global_load_dword v93, v[2:3], off nt
	s_cmp_eq_u64 s[10:11], 0
	s_cbranch_scc1 .LBB0_300
	v_add_u32_e32 v2, s16, v0
	v_ashrrev_i32_e32 v3, 31, v2
	v_lshl_add_u64 v[2:3], v[2:3], 2, s[10:11]
	global_load_dword v94, v[2:3], off
	s_branch .LBB0_301

; __device__ __forceinline__ void item_load(const TItem& t, float (&v)[64], float& kv, int lane) {
;     const int nblk = t.N / 64, kb = t.item / nblk, nb = t.item % nblk, k0 = 64 * kb, n0 = 64 * nb;
;     const float* src = t.W + (size_t)k0 * t.N + n0 + lane;
; #pragma unroll
;     for (int i = 0; i < 64; ++i) v[i] = src[(size_t)i * t.N];
;     kv = t.ks ? t.ks[k0 + lane] : 1.0f;
.LBB0_334:
	v_readlane_b32 s48, v255, 2
	v_readlane_b32 s49, v255, 3
	s_mov_b64 s[4:5], s[48:49]
	s_lshr_b32 s9, s4, 6
	v_cvt_f32_u32_e32 v4, s9
	s_sub_i32 s19, 0, s9
	s_abs_i32 s17, s40
	s_ashr_i32 s16, s40, 31
	v_rcp_iflag_f32_e32 v4, v4
	v_readlane_b32 s50, v255, 4
	v_readlane_b32 s51, v255, 5
	v_mul_f32_e32 v4, 0x4f7ffffe, v4
	v_cvt_u32_f32_e32 v4, v4
	s_nop 0
	v_readfirstlane_b32 s22, v4
	s_mul_i32 s19, s19, s22
	s_mul_hi_u32 s19, s22, s19
	s_add_i32 s22, s22, s19
	s_mul_hi_u32 s19, s17, s22
	s_mul_i32 s22, s19, s9
	s_sub_i32 s17, s17, s22
	s_add_i32 s22, s19, 1
	s_sub_i32 s23, s17, s9
	s_cmp_ge_u32 s17, s9
	s_cselect_b32 s19, s22, s19
	s_cselect_b32 s17, s23, s17
	s_add_i32 s22, s19, 1
	s_cmp_ge_u32 s17, s9
	s_cselect_b32 s17, s22, s19
	s_xor_b32 s17, s17, s16
	s_sub_i32 s16, s17, s16
	s_mul_i32 s9, s16, s9
	s_sub_i32 s17, s40, s9
	s_lshl_b32 s9, s16, 6
	s_lshl_b32 s16, s17, 6
	s_ashr_i32 s17, s9, 31
	s_mul_i32 s17, s17, s4
	s_mul_hi_u32 s19, s9, s4
	s_add_i32 s23, s19, s17
	s_mul_i32 s22, s9, s4
	s_lshl_b64 s[22:23], s[22:23], 2
	s_add_u32 s19, s10, s22
	s_addc_u32 s22, s11, s23
	s_ashr_i32 s17, s16, 31
	s_lshl_b64 s[10:11], s[16:17], 2
	s_add_u32 s10, s19, s10
	s_addc_u32 s11, s22, s11
	v_lshl_add_u64 v[4:5], v[0:1], 2, s[10:11]
	s_lshl_b64 s[10:11], s[48:49], 2
	global_load_dword v28, v[4:5], off nt
	v_lshl_add_u64 v[4:5], v[4:5], 0, s[10:11]
	global_load_dword v29, v[4:5], off nt
	v_lshl_add_u64 v[4:5], v[4:5], 0, s[10:11]
	global_load_dword v30, v[4:5], off nt
	v_lshl_add_u64 v[4:5], v[4:5], 0, s[10:11]
	global_load_dword v31, v[4:5], off nt
	v_lshl_add_u64 v[4:5], v[4:5], 0, s[10:11]
	global_load_dword v34, v[4:5], off nt
	v_lshl_add_u64 v[4:5], v[4:5], 0, s[10:11]
	global_load_dword v35, v[4:5], off nt
	v_lshl_add_u64 v[4:5], v[4:5], 0, s[10:11]
	global_load_dword v36, v[4:5], off nt
	v_lshl_add_u64 v[4:5], v[4:5], 0, s[10:11]
	global_load_dword v37, v[4:5], off nt
	v_lshl_add_u64 v[4:5], v[4:5], 0, s[10:11]
	global_load_dword v38, v[4:5], off nt
	v_lshl_add_u64 v[4:5], v[4:5], 0, s[10:11]
	global_load_dword v39, v[4:5], off nt
	v_lshl_add_u64 v[4:5], v[4:5], 0, s[10:11]
	global_load_dword v40, v[4:5], off nt
	v_lshl_add_u64 v[4:5], v[4:5], 0, s[10:11]
	global_load_dword v41, v[4:5], off nt
	v_lshl_add_u64 v[4:5], v[4:5], 0, s[10:11]
	global_load_dword v42, v[4:5], off nt
	v_lshl_add_u64 v[4:5], v[4:5], 0, s[10:11]
	global_load_dword v43, v[4:5], off nt
	v_lshl_add_u64 v[4:5], v[4:5], 0, s[10:11]
	global_load_dword v44, v[4:5], off nt
	v_lshl_add_u64 v[4:5], v[4:5], 0, s[10:11]
	global_load_dword v45, v[4:5], off nt
	v_lshl_add_u64 v[4:5], v[4:5], 0, s[10:11]
	global_load_dword v46, v[4:5], off nt
	v_lshl_add_u64 v[4:5], v[4:5], 0, s[10:11]
	global_load_dword v47, v[4:5], off nt
	v_lshl_add_u64 v[4:5], v[4:5], 0, s[10:11]
	global_load_dword v48, v[4:5], off nt
	v_lshl_add_u64 v[4:5], v[4:5], 0, s[10:11]
	global_load_dword v49, v[4:5], off nt
	v_lshl_add_u64 v[4:5], v[4:5], 0, s[10:11]
	global_load_dword v50, v[4:5], off nt
	v_lshl_add_u64 v[4:5], v[4:5], 0, s[10:11]
	global_load_dword v51, v[4:5], off nt
	v_lshl_add_u64 v[4:5], v[4:5], 0, s[10:11]
	global_load_dword v52, v[4:5], off nt
	v_lshl_add_u64 v[4:5], v[4:5], 0, s[10:11]
	global_load_dword v53, v[4:5], off nt
	v_lshl_add_u64 v[4:5], v[4:5], 0, s[10:11]
	global_load_dword v54, v[4:5], off nt
	v_lshl_add_u64 v[4:5], v[4:5], 0, s[10:11]
	global_load_dword v55, v[4:5], off nt
	v_lshl_add_u64 v[4:5], v[4:5], 0, s[10:11]
	global_load_dword v56, v[4:5], off nt
	v_lshl_add_u64 v[4:5], v[4:5], 0, s[10:11]
	global_load_dword v57, v[4:5], off nt
	v_lshl_add_u64 v[4:5], v[4:5], 0, s[10:11]
	global_load_dword v58, v[4:5], off nt
	v_lshl_add_u64 v[4:5], v[4:5], 0, s[10:11]
	global_load_dword v59, v[4:5], off nt
	v_lshl_add_u64 v[4:5], v[4:5], 0, s[10:11]
	global_load_dword v60, v[4:5], off nt
	v_lshl_add_u64 v[4:5], v[4:5], 0, s[10:11]
	global_load_dword v61, v[4:5], off nt
	v_lshl_add_u64 v[4:5], v[4:5], 0, s[10:11]
	global_load_dword v62, v[4:5], off nt
	v_lshl_add_u64 v[4:5], v[4:5], 0, s[10:11]
	global_load_dword v63, v[4:5], off nt
	v_lshl_add_u64 v[4:5], v[4:5], 0, s[10:11]
	global_load_dword v64, v[4:5], off nt
	v_lshl_add_u64 v[4:5], v[4:5], 0, s[10:11]
	global_load_dword v65, v[4:5], off nt
	v_lshl_add_u64 v[4:5], v[4:5], 0, s[10:11]
	global_load_dword v66, v[4:5], off nt
	v_lshl_add_u64 v[4:5], v[4:5], 0, s[10:11]
	global_load_dword v67, v[4:5], off nt
	v_lshl_add_u64 v[4:5], v[4:5], 0, s[10:11]
	global_load_dword v68, v[4:5], off nt
	v_lshl_add_u64 v[4:5], v[4:5], 0, s[10:11]
	global_load_dword v69, v[4:5], off nt
	v_lshl_add_u64 v[4:5], v[4:5], 0, s[10:11]
	global_load_dword v70, v[4:5], off nt
	v_lshl_add_u64 v[4:5], v[4:5], 0, s[10:11]
	global_load_dword v71, v[4:5], off nt
	v_lshl_add_u64 v[4:5], v[4:5], 0, s[10:11]
	global_load_dword v72, v[4:5], off nt
	v_lshl_add_u64 v[4:5], v[4:5], 0, s[10:11]
	global_load_dword v73, v[4:5], off nt
	v_lshl_add_u64 v[4:5], v[4:5], 0, s[10:11]
	global_load_dword v74, v[4:5], off nt
	v_lshl_add_u64 v[4:5], v[4:5], 0, s[10:11]
	global_load_dword v75, v[4:5], off nt
	v_lshl_add_u64 v[4:5], v[4:5], 0, s[10:11]
	global_load_dword v76, v[4:5], off nt
	v_lshl_add_u64 v[4:5], v[4:5], 0, s[10:11]
	global_load_dword v77, v[4:5], off nt
	v_lshl_add_u64 v[4:5], v[4:5], 0, s[10:11]
	global_load_dword v78, v[4:5], off nt
	v_lshl_add_u64 v[4:5], v[4:5], 0, s[10:11]
	global_load_dword v79, v[4:5], off nt
	v_lshl_add_u64 v[4:5], v[4:5], 0, s[10:11]
	global_load_dword v80, v[4:5], off nt
	v_lshl_add_u64 v[4:5], v[4:5], 0, s[10:11]
	global_load_dword v81, v[4:5], off nt
	v_lshl_add_u64 v[4:5], v[4:5], 0, s[10:11]
	global_load_dword v82, v[4:5], off nt
	v_lshl_add_u64 v[4:5], v[4:5], 0, s[10:11]
	global_load_dword v83, v[4:5], off nt
	v_lshl_add_u64 v[4:5], v[4:5], 0, s[10:11]
	global_load_dword v84, v[4:5], off nt
	v_lshl_add_u64 v[4:5], v[4:5], 0, s[10:11]
	global_load_dword v85, v[4:5], off nt
	v_lshl_add_u64 v[4:5], v[4:5], 0, s[10:11]
	global_load_dword v86, v[4:5], off nt
	v_lshl_add_u64 v[4:5], v[4:5], 0, s[10:11]
	global_load_dword v87, v[4:5], off nt
	v_lshl_add_u64 v[4:5], v[4:5], 0, s[10:11]
	global_load_dword v88, v[4:5], off nt
	v_lshl_add_u64 v[4:5], v[4:5], 0, s[10:11]
	global_load_dword v89, v[4:5], off nt
	v_lshl_add_u64 v[4:5], v[4:5], 0, s[10:11]
	global_load_dword v90, v[4:5], off nt
	v_lshl_add_u64 v[4:5], v[4:5], 0, s[10:11]
	global_load_dword v91, v[4:5], off nt
	v_lshl_add_u64 v[4:5], v[4:5], 0, s[10:11]
	global_load_dword v92, v[4:5], off nt
	v_lshl_add_u64 v[4:5], v[4:5], 0, s[10:11]
	global_load_dword v93, v[4:5], off nt
	s_mov_b64 s[10:11], 0
	s_cmp_eq_u64 s[26:27], 0
	s_cbranch_scc1 .LBB0_337
	v_add_u32_e32 v4, s9, v0
	v_ashrrev_i32_e32 v5, 31, v4
	v_lshl_add_u64 v[4:5], v[4:5], 2, s[26:27]
	global_load_dword v94, v[4:5], off
	s_mov_b64 s[10:11], s[26:27]
	s_branch .LBB0_338
